# P5+P6 fused like P12+P13: x1b written from f32 accumulators after the barrier, partial sum(x1^2) via dead mix buffer, rstd1 derived per tile at P7 start; P6 loop handles sample rows only
# speedup vs baseline: 1.0071x; 1.0071x over previous
.LBB0_784:
	s_nop 7
	v_xor_b32_e32 v138, 16, v137
	v_xor_b32_e32 v139, 32, v137
	v_lshlrev_b32_e32 v138, 2, v138
	v_lshlrev_b32_e32 v139, 2, v139
	v_mul_f32_e32 v140, v124, v124
	v_mul_f32_e32 v141, v108, v108
	v_mul_f32_e32 v142, v92, v92
	v_mul_f32_e32 v143, v76, v76
	v_mul_f32_e32 v144, v60, v60
	v_mul_f32_e32 v145, v44, v44
	v_mul_f32_e32 v146, v28, v28
	v_mul_f32_e32 v147, v12, v12
	v_fmac_f32_e32 v140, v125, v125
	v_fmac_f32_e32 v141, v109, v109
	v_fmac_f32_e32 v142, v93, v93
	v_fmac_f32_e32 v143, v77, v77
	v_fmac_f32_e32 v144, v61, v61
	v_fmac_f32_e32 v145, v45, v45
	v_fmac_f32_e32 v146, v29, v29
	v_fmac_f32_e32 v147, v13, v13
	v_fmac_f32_e32 v140, v126, v126
	v_fmac_f32_e32 v141, v110, v110
	v_fmac_f32_e32 v142, v94, v94
	v_fmac_f32_e32 v143, v78, v78
	v_fmac_f32_e32 v144, v62, v62
	v_fmac_f32_e32 v145, v46, v46
	v_fmac_f32_e32 v146, v30, v30
	v_fmac_f32_e32 v147, v14, v14
	v_fmac_f32_e32 v140, v127, v127
	v_fmac_f32_e32 v141, v111, v111
	v_fmac_f32_e32 v142, v95, v95
	v_fmac_f32_e32 v143, v79, v79
	v_fmac_f32_e32 v144, v63, v63
	v_fmac_f32_e32 v145, v47, v47
	v_fmac_f32_e32 v146, v31, v31
	v_fmac_f32_e32 v147, v15, v15
	v_fmac_f32_e32 v140, v112, v112
	v_fmac_f32_e32 v141, v96, v96
	v_fmac_f32_e32 v142, v80, v80
	v_fmac_f32_e32 v143, v64, v64
	v_fmac_f32_e32 v144, v48, v48
	v_fmac_f32_e32 v145, v32, v32
	v_fmac_f32_e32 v146, v16, v16
	v_fmac_f32_e32 v147, v0, v0
	v_fmac_f32_e32 v140, v113, v113
	v_fmac_f32_e32 v141, v97, v97
	v_fmac_f32_e32 v142, v81, v81
	v_fmac_f32_e32 v143, v65, v65
	v_fmac_f32_e32 v144, v49, v49
	v_fmac_f32_e32 v145, v33, v33
	v_fmac_f32_e32 v146, v17, v17
	v_fmac_f32_e32 v147, v1, v1
	v_fmac_f32_e32 v140, v114, v114
	v_fmac_f32_e32 v141, v98, v98
	v_fmac_f32_e32 v142, v82, v82
	v_fmac_f32_e32 v143, v66, v66
	v_fmac_f32_e32 v144, v50, v50
	v_fmac_f32_e32 v145, v34, v34
	v_fmac_f32_e32 v146, v18, v18
	v_fmac_f32_e32 v147, v2, v2
	v_fmac_f32_e32 v140, v115, v115
	v_fmac_f32_e32 v141, v99, v99
	v_fmac_f32_e32 v142, v83, v83
	v_fmac_f32_e32 v143, v67, v67
	v_fmac_f32_e32 v144, v51, v51
	v_fmac_f32_e32 v145, v35, v35
	v_fmac_f32_e32 v146, v19, v19
	v_fmac_f32_e32 v147, v3, v3
	v_fmac_f32_e32 v140, v120, v120
	v_fmac_f32_e32 v141, v100, v100
	v_fmac_f32_e32 v142, v84, v84
	v_fmac_f32_e32 v143, v68, v68
	v_fmac_f32_e32 v144, v52, v52
	v_fmac_f32_e32 v145, v36, v36
	v_fmac_f32_e32 v146, v20, v20
	v_fmac_f32_e32 v147, v4, v4
	v_fmac_f32_e32 v140, v121, v121
	v_fmac_f32_e32 v141, v101, v101
	v_fmac_f32_e32 v142, v85, v85
	v_fmac_f32_e32 v143, v69, v69
	v_fmac_f32_e32 v144, v53, v53
	v_fmac_f32_e32 v145, v37, v37
	v_fmac_f32_e32 v146, v21, v21
	v_fmac_f32_e32 v147, v5, v5
	v_fmac_f32_e32 v140, v122, v122
	v_fmac_f32_e32 v141, v102, v102
	v_fmac_f32_e32 v142, v86, v86
	v_fmac_f32_e32 v143, v70, v70
	v_fmac_f32_e32 v144, v54, v54
	v_fmac_f32_e32 v145, v38, v38
	v_fmac_f32_e32 v146, v22, v22
	v_fmac_f32_e32 v147, v6, v6
	v_fmac_f32_e32 v140, v123, v123
	v_fmac_f32_e32 v141, v103, v103
	v_fmac_f32_e32 v142, v87, v87
	v_fmac_f32_e32 v143, v71, v71
	v_fmac_f32_e32 v144, v55, v55
	v_fmac_f32_e32 v145, v39, v39
	v_fmac_f32_e32 v146, v23, v23
	v_fmac_f32_e32 v147, v7, v7
	v_fmac_f32_e32 v140, v116, v116
	v_fmac_f32_e32 v141, v104, v104
	v_fmac_f32_e32 v142, v88, v88
	v_fmac_f32_e32 v143, v72, v72
	v_fmac_f32_e32 v144, v56, v56
	v_fmac_f32_e32 v145, v40, v40
	v_fmac_f32_e32 v146, v24, v24
	v_fmac_f32_e32 v147, v8, v8
	v_fmac_f32_e32 v140, v117, v117
	v_fmac_f32_e32 v141, v105, v105
	v_fmac_f32_e32 v142, v89, v89
	v_fmac_f32_e32 v143, v73, v73
	v_fmac_f32_e32 v144, v57, v57
	v_fmac_f32_e32 v145, v41, v41
	v_fmac_f32_e32 v146, v25, v25
	v_fmac_f32_e32 v147, v9, v9
	v_fmac_f32_e32 v140, v118, v118
	v_fmac_f32_e32 v141, v106, v106
	v_fmac_f32_e32 v142, v90, v90
	v_fmac_f32_e32 v143, v74, v74
	v_fmac_f32_e32 v144, v58, v58
	v_fmac_f32_e32 v145, v42, v42
	v_fmac_f32_e32 v146, v26, v26
	v_fmac_f32_e32 v147, v10, v10
	v_fmac_f32_e32 v140, v119, v119
	v_fmac_f32_e32 v141, v107, v107
	v_fmac_f32_e32 v142, v91, v91
	v_fmac_f32_e32 v143, v75, v75
	v_fmac_f32_e32 v144, v59, v59
	v_fmac_f32_e32 v145, v43, v43
	v_fmac_f32_e32 v146, v27, v27
	v_fmac_f32_e32 v147, v11, v11
	ds_bpermute_b32 v148, v138, v140
	ds_bpermute_b32 v149, v138, v141
	ds_bpermute_b32 v150, v138, v142
	ds_bpermute_b32 v151, v138, v143
	ds_bpermute_b32 v152, v138, v144
	ds_bpermute_b32 v153, v138, v145
	ds_bpermute_b32 v154, v138, v146
	ds_bpermute_b32 v155, v138, v147
	s_waitcnt lgkmcnt(0)
	v_add_f32_e32 v140, v140, v148
	v_add_f32_e32 v141, v141, v149
	v_add_f32_e32 v142, v142, v150
	v_add_f32_e32 v143, v143, v151
	v_add_f32_e32 v144, v144, v152
	v_add_f32_e32 v145, v145, v153
	v_add_f32_e32 v146, v146, v154
	v_add_f32_e32 v147, v147, v155
	ds_bpermute_b32 v148, v139, v140
	ds_bpermute_b32 v149, v139, v141
	ds_bpermute_b32 v150, v139, v142
	ds_bpermute_b32 v151, v139, v143
	ds_bpermute_b32 v152, v139, v144
	ds_bpermute_b32 v153, v139, v145
	ds_bpermute_b32 v154, v139, v146
	ds_bpermute_b32 v155, v139, v147
	s_waitcnt lgkmcnt(0)
	v_add_f32_e32 v140, v140, v148
	v_add_f32_e32 v141, v141, v149
	v_add_f32_e32 v142, v142, v150
	v_add_f32_e32 v143, v143, v151
	v_add_f32_e32 v144, v144, v152
	v_add_f32_e32 v145, v145, v153
	v_add_f32_e32 v146, v146, v154
	v_add_f32_e32 v147, v147, v155
	s_and_b32 s98, s2, 7
	s_lshl_b32 s98, s98, 3
	s_bfe_u32 s99, s2, 0x30003
	s_or_b32 s98, s98, s99
	s_lshr_b32 s99, s2, 6
	s_mul_i32 s99, s99, 0x42000
	s_lshl_b32 s98, s98, 10
	s_add_u32 s100, s44, s99
	s_addc_u32 s101, s45, 0
	s_add_u32 s100, s100, s98
	s_addc_u32 s101, s101, 0
	v_lshrrev_b32_e32 v158, 8, v136
	v_bfe_u32 v159, v136, 6, 2
	v_and_b32_e32 v160, 15, v136
	v_lshl_add_u32 v160, v158, 6, v160
	v_mul_u32_u24_e32 v159, 0x4200, v159
	v_add_u32_e32 v160, v160, v159
	v_lshlrev_b32_e32 v160, 2, v160
	v_bfe_u32 v161, v136, 4, 2
	v_cmp_eq_u32_e32 vcc, 0, v161
	s_and_saveexec_b64 s[0:1], vcc
	global_store_dword v160, v140, s[100:101]
	global_store_dword v160, v141, s[100:101] offset:64
	global_store_dword v160, v142, s[100:101] offset:128
	global_store_dword v160, v143, s[100:101] offset:192
	global_store_dword v160, v144, s[100:101] offset:512
	global_store_dword v160, v145, s[100:101] offset:576
	global_store_dword v160, v146, s[100:101] offset:640
	global_store_dword v160, v147, s[100:101] offset:704
	s_or_b64 exec, exec, s[0:1]
	s_branch .LBB0_776
.LBB0_800:
	s_waitcnt vmcnt(0)
	s_waitcnt vmcnt(0) lgkmcnt(0)
	s_barrier
	s_mov_b64 s[0:1], exec
	v_readlane_b32 s4, v253, 1
	v_readlane_b32 s5, v253, 2
	s_and_b64 s[4:5], s[0:1], s[4:5]
	s_mov_b64 exec, s[4:5]
	s_cbranch_execz .LBB0_852
	s_add_i32 s3, 0, 0x20000
	v_mov_b32_e32 v140, s3
	s_waitcnt vmcnt(0) expcnt(0) lgkmcnt(0)
	ds_read_b32 v142, v140
	s_add_i32 s3, 0, 0x20004
	v_mov_b32_e32 v140, s3
	ds_read_b32 v140, v140
	s_waitcnt lgkmcnt(1)
	v_cmp_ne_u32_e32 vcc, 0, v142
	s_cbranch_vccnz .LBB0_816
	s_add_u32 s4, s54, 0x1000
	s_addc_u32 s5, s55, 0
	s_add_u32 s6, s54, 0x1100
	s_addc_u32 s7, s55, 0
	s_add_u32 s8, s54, 0x1200
	v_readlane_b32 s3, v253, 0
	s_addc_u32 s9, s55, 0
	s_mul_i32 s3, s39, s3
	s_add_u32 s12, s54, 0x1300
	s_mul_i32 s3, s3, s38
	s_addc_u32 s13, s55, 0
	s_mov_b32 s20, 1
	v_mov_b32_e32 v156, 0
	s_branch .LBB0_804

.LBB0_804:
	global_load_dword v155, v156, s[54:55] offset:1024 sc1
	s_waitcnt lgkmcnt(0)
	global_load_dword v140, v156, s[54:55] offset:1280 sc1
	global_load_dword v141, v156, s[54:55] offset:1536 sc1
	global_load_dword v142, v156, s[54:55] offset:1792 sc1
	global_load_dword v143, v156, s[54:55] offset:2048 sc1
	global_load_dword v144, v156, s[54:55] offset:2304 sc1
	global_load_dword v145, v156, s[54:55] offset:2560 sc1
	global_load_dword v146, v156, s[54:55] offset:2816 sc1
	global_load_dword v147, v156, s[54:55] offset:3072 sc1
	global_load_dword v148, v156, s[54:55] offset:3328 sc1
	global_load_dword v149, v156, s[54:55] offset:3584 sc1
	global_load_dword v150, v156, s[54:55] offset:3840 sc1
	global_load_dword v151, v156, s[4:5] sc1
	global_load_dword v152, v156, s[6:7] sc1
	global_load_dword v153, v156, s[8:9] sc1
	global_load_dword v154, v156, s[12:13] sc1
	s_mov_b64 s[14:15], -1
	s_mov_b64 s[16:17], -1
	s_waitcnt vmcnt(14)
	v_add_u32_e32 v157, v140, v155
	s_waitcnt vmcnt(13)
	v_add_u32_e32 v157, v157, v141
	s_waitcnt vmcnt(12)
	v_add_u32_e32 v157, v157, v142
	s_waitcnt vmcnt(11)
	v_add_u32_e32 v157, v157, v143
	s_waitcnt vmcnt(10)
	v_add_u32_e32 v157, v157, v144
	s_waitcnt vmcnt(9)
	v_add_u32_e32 v157, v157, v145
	s_waitcnt vmcnt(8)
	v_add_u32_e32 v157, v157, v146
	s_waitcnt vmcnt(7)
	v_add_u32_e32 v157, v157, v147
	s_waitcnt vmcnt(6)
	v_add_u32_e32 v157, v157, v148
	s_waitcnt vmcnt(5)
	v_add_u32_e32 v157, v157, v149
	s_waitcnt vmcnt(4)
	v_add_u32_e32 v157, v157, v150
	s_waitcnt vmcnt(3)
	v_add_u32_e32 v157, v157, v151
	s_waitcnt vmcnt(2)
	v_add_u32_e32 v157, v157, v152
	s_waitcnt vmcnt(1)
	v_add_u32_e32 v157, v157, v153
	s_waitcnt vmcnt(0)
	v_add_u32_e32 v157, v157, v154
	v_cmp_eq_u32_e32 vcc, s3, v157
	s_cbranch_vccnz .LBB0_803
	s_and_b32 s14, s20, 0xff
	s_cmp_eq_u32 s14, 0
	s_mov_b64 s[14:15], -1
	s_mov_b64 s[18:19], -1
	s_sleep 1
	s_cbranch_scc1 .LBB0_808
	s_and_b64 vcc, exec, s[18:19]
	s_cbranch_vccz .LBB0_803

.LBB0_811:
	s_andn2_b64 vcc, exec, s[14:15]
	s_cbranch_vccz .LBB0_815
	s_mov_b64 s[6:7], exec
	v_mbcnt_lo_u32_b32 v156, s6, 0
	v_mbcnt_hi_u32_b32 v156, s7, v156
	v_cmp_eq_u32_e32 vcc, 0, v156
	s_and_saveexec_b64 s[4:5], vcc
	s_cbranch_execz .LBB0_814
	s_bcnt1_i32_b64 s3, s[6:7]
	v_mov_b32_e32 v156, 0
	v_mov_b32_e32 v157, s3
	global_atomic_add v156, v157, s[54:55] offset:512

.LBB0_816:
	s_mov_b64 s[6:7], exec
	v_readlane_b32 s3, v254, 3
	s_lshl_b32 s3, s3, 8
	v_mbcnt_lo_u32_b32 v141, s6, 0
	s_add_u32 s4, s54, s3
	v_mbcnt_hi_u32_b32 v141, s7, v141
	s_addc_u32 s5, s55, 0
	v_cmp_eq_u32_e32 vcc, 0, v141
	s_and_saveexec_b64 s[8:9], vcc
	s_cbranch_execz .LBB0_818
	s_bcnt1_i32_b64 s3, s[6:7]
	v_mov_b32_e32 v143, 0x1000
	v_mov_b32_e32 v144, s3
	global_atomic_add v143, v143, v144, s[4:5] offset:1024 sc0
.LBB0_818:
	s_or_b64 exec, exec, s[8:9]
	v_cvt_f32_u32_e32 v144, v142
	s_waitcnt vmcnt(0)
	v_readfirstlane_b32 s3, v143
	v_sub_u32_e32 v143, 0, v142
	v_rcp_iflag_f32_e32 v144, v144
	v_add_u32_e32 v145, s3, v141
	v_mul_f32_e32 v144, 0x4f7ffffe, v144
	v_cvt_u32_f32_e32 v144, v144
	v_mul_lo_u32 v141, v143, v144
	v_mul_hi_u32 v141, v144, v141
	v_add_u32_e32 v141, v144, v141
	v_mul_hi_u32 v141, v145, v141
	v_mul_lo_u32 v143, v141, v142
	v_sub_u32_e32 v143, v145, v143
	v_add_u32_e32 v144, 1, v141
	v_cmp_ge_u32_e32 vcc, v143, v142
	s_nop 1
	v_cndmask_b32_e32 v141, v141, v144, vcc
	v_sub_u32_e32 v144, v143, v142
	v_cndmask_b32_e32 v143, v143, v144, vcc
	v_add_u32_e32 v144, 1, v141
	v_cmp_ge_u32_e32 vcc, v143, v142
	v_add_u32_e32 v143, 1, v145
	s_nop 0
	v_cndmask_b32_e32 v141, v141, v144, vcc
	v_mul_lo_u32 v144, v142, v141
	v_add_u32_e32 v142, v144, v142
	v_cmp_ne_u32_e32 vcc, v143, v142
	s_and_saveexec_b64 s[6:7], vcc
	s_xor_b64 s[6:7], exec, s[6:7]
	s_cbranch_execz .LBB0_832
	s_waitcnt lgkmcnt(0)
	v_mov_b32_e32 v140, 0x2000
	global_load_dword v140, v140, s[4:5] offset:1024 sc1
	s_add_u32 s12, s4, 0x2400
	s_addc_u32 s13, s5, 0
	s_waitcnt vmcnt(0)
	v_cmp_eq_u32_e32 vcc, v140, v141
	s_and_saveexec_b64 s[8:9], vcc
	s_cbranch_execz .LBB0_831
	s_mov_b32 s3, 1
	s_mov_b64 s[14:15], 0
	v_mov_b32_e32 v140, 0
	s_branch .LBB0_822

.LBB0_828:
	s_or_b64 exec, exec, s[14:15]
	s_xor_b64 s[12:13], s[16:17], -1
	s_and_saveexec_b64 s[14:15], s[12:13]
	s_xor_b64 s[14:15], exec, s[14:15]
	s_cbranch_execz .LBB0_831
	s_mov_b64 s[12:13], exec
	v_mbcnt_lo_u32_b32 v140, s12, 0
	v_mbcnt_hi_u32_b32 v140, s13, v140
	v_cmp_eq_u32_e32 vcc, 0, v140
	s_and_b64 s[14:15], exec, vcc
	s_mov_b64 exec, s[14:15]
	s_cbranch_execz .LBB0_831
	s_bcnt1_i32_b64 s3, s[12:13]
	v_mov_b32_e32 v140, 0
	v_mov_b32_e32 v141, s3
	global_atomic_add v140, v141, s[54:55] offset:512
.LBB0_831:
	s_or_b64 exec, exec, s[8:9]
	s_waitcnt vmcnt(0)
	buffer_inv sc1
	s_waitcnt vmcnt(0)
.LBB0_832:
	s_andn2_saveexec_b64 s[6:7], s[6:7]
	s_cbranch_execz .LBB0_852
	s_mov_b64 s[6:7], exec
	buffer_wbl2 sc1
	s_waitcnt lgkmcnt(0)
	s_waitcnt vmcnt(0)
	v_mbcnt_lo_u32_b32 v141, s6, 0
	v_mbcnt_hi_u32_b32 v141, s7, v141
	v_cmp_eq_u32_e32 vcc, 0, v141
	s_and_saveexec_b64 s[8:9], vcc
	s_cbranch_execz .LBB0_835
	s_bcnt1_i32_b64 s3, s[6:7]
	v_mov_b32_e32 v142, 0x3000
	v_mov_b32_e32 v143, s3
	global_atomic_add v142, v142, v143, s[54:55] offset:1024 sc0
.LBB0_835:
	s_or_b64 exec, exec, s[8:9]
	v_cvt_f32_u32_e32 v143, v140
	s_waitcnt vmcnt(0)
	v_readfirstlane_b32 s3, v142
	s_add_u32 s8, s54, 0x3500
	s_addc_u32 s9, s55, 0
	v_rcp_iflag_f32_e32 v143, v143
	v_add_u32_e32 v141, s3, v141
	v_add_u32_e32 v144, 1, v141
	s_mov_b64 s[12:13], -1
	v_mul_f32_e32 v142, 0x4f7ffffe, v143
	v_cvt_u32_f32_e32 v142, v142
	v_sub_u32_e32 v143, 0, v140
	v_mul_lo_u32 v143, v143, v142
	v_mul_hi_u32 v143, v142, v143
	v_add_u32_e32 v142, v142, v143
	v_mul_hi_u32 v142, v141, v142
	v_mul_lo_u32 v143, v142, v140
	v_sub_u32_e32 v141, v141, v143
	v_add_u32_e32 v145, 1, v142
	v_cmp_ge_u32_e32 vcc, v141, v140
	v_sub_u32_e32 v143, v141, v140
	s_nop 0
	v_cndmask_b32_e32 v142, v142, v145, vcc
	v_cndmask_b32_e32 v141, v141, v143, vcc
	v_add_u32_e32 v143, 1, v142
	v_cmp_ge_u32_e32 vcc, v141, v140
	s_nop 1
	v_cndmask_b32_e32 v142, v142, v143, vcc
	v_mul_lo_u32 v141, v140, v142
	v_add_u32_e32 v140, v141, v140
	v_cmp_ne_u32_e32 vcc, v144, v140
	v_mov_b64_e32 v[140:141], s[8:9]
	s_and_saveexec_b64 s[6:7], vcc
	s_cbranch_execz .LBB0_847
	v_mov_b32_e32 v140, 0
	global_load_dword v141, v140, s[8:9] sc1
	s_mov_b64 s[16:17], 0
	s_waitcnt vmcnt(0)
	v_cmp_eq_u32_e32 vcc, v141, v142
	s_and_saveexec_b64 s[14:15], vcc
	s_cbranch_execz .LBB0_846
	s_add_u32 s12, s54, 0x200
	s_addc_u32 s13, s55, 0
	s_mov_b32 s3, 1
	s_branch .LBB0_839

.LBB0_841:
	global_load_dword v141, v140, s[8:9] sc1
	s_add_i32 s3, s3, 1
	s_mov_b64 s[20:21], -1
	s_waitcnt vmcnt(0)
	v_cmp_ne_u32_e32 vcc, v141, v142
	s_orn2_b64 s[24:25], vcc, exec
	s_branch .LBB0_838

.LBB0_847:
	s_or_b64 exec, exec, s[6:7]
	s_and_saveexec_b64 s[6:7], s[12:13]
	s_cbranch_execz .LBB0_849
	v_mov_b32_e32 v142, 1
	global_atomic_add v[140:141], v142, off
.LBB0_849:
	s_or_b64 exec, exec, s[6:7]
	s_mov_b64 s[6:7], exec
	v_mbcnt_lo_u32_b32 v140, s6, 0
	v_mbcnt_hi_u32_b32 v140, s7, v140
	v_cmp_eq_u32_e32 vcc, 0, v140
	s_waitcnt vmcnt(0)
	buffer_inv sc1
	s_and_saveexec_b64 s[8:9], vcc
	s_cbranch_execz .LBB0_851
	s_bcnt1_i32_b64 s3, s[6:7]
	v_mov_b32_e32 v140, 0x2000
	v_mov_b32_e32 v141, s3
	global_atomic_add v140, v141, s[4:5] offset:1024

.LBB0_852:
	s_or_b64 exec, exec, s[0:1]
	s_waitcnt lgkmcnt(0)
	s_barrier
	s_and_b32 s98, s2, 7
	s_lshl_b32 s98, s98, 3
	s_bfe_u32 s99, s2, 0x30003
	s_or_b32 s98, s98, s99
	s_lshr_b32 s99, s2, 6
	v_and_b32_e32 v138, 0xff, v136
	v_lshrrev_b32_e32 v139, 8, v136
	v_mul_u32_u24_e32 v139, 0x84000, v139
	v_lshl_add_u32 v138, v138, 2, v139
	s_lshl_b32 s24, s98, 10
	s_add_u32 s18, s44, s24
	s_addc_u32 s19, s45, 0
	global_load_dword v140, v138, s[18:19]
	s_add_u32 s18, s18, 0x10800
	s_addc_u32 s19, s19, 0
	global_load_dword v141, v138, s[18:19]
	s_add_u32 s18, s18, 0x10800
	s_addc_u32 s19, s19, 0
	global_load_dword v142, v138, s[18:19]
	s_add_u32 s18, s18, 0x10800
	s_addc_u32 s19, s19, 0
	global_load_dword v143, v138, s[18:19]
	s_add_u32 s18, s18, 0x10800
	s_addc_u32 s19, s19, 0
	global_load_dword v144, v138, s[18:19]
	s_add_u32 s18, s18, 0x10800
	s_addc_u32 s19, s19, 0
	global_load_dword v145, v138, s[18:19]
	s_add_u32 s18, s18, 0x10800
	s_addc_u32 s19, s19, 0
	global_load_dword v146, v138, s[18:19]
	s_add_u32 s18, s18, 0x10800
	s_addc_u32 s19, s19, 0
	global_load_dword v147, v138, s[18:19]
	s_waitcnt vmcnt(0)
	v_add_f32_e32 v140, v140, v141
	v_add_f32_e32 v140, v140, v142
	v_add_f32_e32 v140, v140, v143
	v_add_f32_e32 v140, v140, v144
	v_add_f32_e32 v140, v140, v145
	v_add_f32_e32 v140, v140, v146
	v_add_f32_e32 v140, v140, v147
	v_lshlrev_b32_e32 v139, 2, v136
	ds_write_b32 v139, v140
	s_waitcnt lgkmcnt(0)
	s_barrier
	v_lshrrev_b32_e32 v141, 8, v136
	v_and_b32_e32 v142, 15, v136
	v_lshl_add_u32 v141, v141, 6, v142
	v_lshlrev_b32_e32 v142, 2, v141
	ds_read_b32 v128, v142 offset:0
	ds_read_b32 v148, v142 offset:1024
	ds_read_b32 v129, v142 offset:64
	ds_read_b32 v149, v142 offset:1088
	ds_read_b32 v130, v142 offset:128
	ds_read_b32 v150, v142 offset:1152
	ds_read_b32 v131, v142 offset:192
	ds_read_b32 v151, v142 offset:1216
	ds_read_b32 v132, v142 offset:512
	ds_read_b32 v152, v142 offset:1536
	ds_read_b32 v133, v142 offset:576
	ds_read_b32 v153, v142 offset:1600
	ds_read_b32 v134, v142 offset:640
	ds_read_b32 v154, v142 offset:1664
	ds_read_b32 v135, v142 offset:704
	ds_read_b32 v155, v142 offset:1728
	s_waitcnt lgkmcnt(0)
	s_mov_b32 s101, 0x3a800000
	v_mov_b32_e32 v143, 0x358637bd
	v_add_f32_e32 v128, v128, v148
	v_add_f32_e32 v129, v129, v149
	v_add_f32_e32 v130, v130, v150
	v_add_f32_e32 v131, v131, v151
	v_add_f32_e32 v132, v132, v152
	v_add_f32_e32 v133, v133, v153
	v_add_f32_e32 v134, v134, v154
	v_add_f32_e32 v135, v135, v155
	v_fma_f32 v128, v128, s101, v143
	v_fma_f32 v129, v129, s101, v143
	v_fma_f32 v130, v130, s101, v143
	v_fma_f32 v131, v131, s101, v143
	v_fma_f32 v132, v132, s101, v143
	v_fma_f32 v133, v133, s101, v143
	v_fma_f32 v134, v134, s101, v143
	v_fma_f32 v135, v135, s101, v143
	v_rsq_f32_e32 v128, v128
	v_rsq_f32_e32 v129, v129
	v_rsq_f32_e32 v130, v130
	v_rsq_f32_e32 v131, v131
	v_rsq_f32_e32 v132, v132
	v_rsq_f32_e32 v133, v133
	v_rsq_f32_e32 v134, v134
	v_rsq_f32_e32 v135, v135
	v_bfe_u32 v144, v136, 6, 2
	v_bfe_u32 v145, v136, 4, 2
	v_lshlrev_b32_e32 v144, 5, v144
	v_lshl_add_u32 v144, v145, 3, v144
	s_lshl_b32 s24, s99, 8
	v_add_u32_e32 v144, s24, v144
	s_lshl_b32 s25, s98, 8
	v_add_u32_e32 v145, s25, v141
	v_lshl_add_u32 v146, v145, 10, v144
	v_lshlrev_b32_e32 v140, 1, v146
	v_lshlrev_b32_e32 v147, 2, v144
	v_readlane_b32 s18, v253, 3
	v_readlane_b32 s19, v253, 4
	v_readlane_b32 s20, v253, 53
	v_readlane_b32 s21, v253, 54
	s_nop 4
	s_add_u32 s18, s18, 0x1000
	s_addc_u32 s19, s19, 0
	global_load_dwordx4 v[148:151], v147, s[18:19]
	global_load_dwordx4 v[152:155], v147, s[18:19] offset:16
	global_load_dwordx4 v[156:159], v147, s[18:19] offset:512
	global_load_dwordx4 v[160:163], v147, s[18:19] offset:528
	s_add_u32 s22, s20, 0x0
	s_addc_u32 s23, s21, 0
	global_load_dwordx4 v[188:191], v140, s[22:23] nt
	global_load_dwordx4 v[192:195], v140, s[22:23] offset:256 nt
	s_add_u32 s22, s20, 0x8000
	s_addc_u32 s23, s21, 0
	global_load_dwordx4 v[196:199], v140, s[22:23] nt
	global_load_dwordx4 v[200:203], v140, s[22:23] offset:256 nt
	s_add_u32 s22, s20, 0x10000
	s_addc_u32 s23, s21, 0
	global_load_dwordx4 v[204:207], v140, s[22:23] nt
	global_load_dwordx4 v[208:211], v140, s[22:23] offset:256 nt
	s_add_u32 s22, s20, 0x18000
	s_addc_u32 s23, s21, 0
	global_load_dwordx4 v[212:215], v140, s[22:23] nt
	global_load_dwordx4 v[216:219], v140, s[22:23] offset:256 nt
	s_add_u32 s22, s20, 0x40000
	s_addc_u32 s23, s21, 0
	global_load_dwordx4 v[220:223], v140, s[22:23] nt
	global_load_dwordx4 v[224:227], v140, s[22:23] offset:256 nt
	s_add_u32 s22, s20, 0x48000
	s_addc_u32 s23, s21, 0
	global_load_dwordx4 v[228:231], v140, s[22:23] nt
	global_load_dwordx4 v[232:235], v140, s[22:23] offset:256 nt
	s_add_u32 s22, s20, 0x50000
	s_addc_u32 s23, s21, 0
	global_load_dwordx4 v[236:239], v140, s[22:23] nt
	global_load_dwordx4 v[240:243], v140, s[22:23] offset:256 nt
	s_add_u32 s22, s20, 0x58000
	s_addc_u32 s23, s21, 0
	global_load_dwordx4 v[244:247], v140, s[22:23] nt
	global_load_dwordx4 v[248:251], v140, s[22:23] offset:256 nt
	s_waitcnt vmcnt(0)
	s_add_u32 s22, s60, 0x0
	s_addc_u32 s23, s61, 0
	v_lshlrev_b32_e32 v164, 16, v188
	v_and_b32_e32 v165, 0xffff0000, v188
	v_lshlrev_b32_e32 v166, 16, v189
	v_and_b32_e32 v167, 0xffff0000, v189
	v_lshlrev_b32_e32 v168, 16, v190
	v_and_b32_e32 v169, 0xffff0000, v190
	v_lshlrev_b32_e32 v170, 16, v191
	v_and_b32_e32 v171, 0xffff0000, v191
	v_mul_f32_e32 v124, v124, v128
	v_mul_f32_e32 v125, v125, v128
	v_mul_f32_e32 v126, v126, v128
	v_mul_f32_e32 v127, v127, v128
	v_mul_f32_e32 v112, v112, v128
	v_mul_f32_e32 v113, v113, v128
	v_mul_f32_e32 v114, v114, v128
	v_mul_f32_e32 v115, v115, v128
	v_fmac_f32_e32 v164, v124, v148
	v_fmac_f32_e32 v165, v125, v149
	v_fmac_f32_e32 v166, v126, v150
	v_fmac_f32_e32 v167, v127, v151
	v_fmac_f32_e32 v168, v112, v152
	v_fmac_f32_e32 v169, v113, v153
	v_fmac_f32_e32 v170, v114, v154
	v_fmac_f32_e32 v171, v115, v155
	v_mul_f32_e32 v138, v164, v164
	v_fmac_f32_e32 v138, v165, v165
	v_fmac_f32_e32 v138, v166, v166
	v_fmac_f32_e32 v138, v167, v167
	v_fmac_f32_e32 v138, v168, v168
	v_fmac_f32_e32 v138, v169, v169
	v_fmac_f32_e32 v138, v170, v170
	v_fmac_f32_e32 v138, v171, v171
	v_cvt_pk_bf16_f32 v180, v164, v165
	v_cvt_pk_bf16_f32 v181, v166, v167
	v_cvt_pk_bf16_f32 v182, v168, v169
	v_cvt_pk_bf16_f32 v183, v170, v171
	global_store_dwordx4 v140, v[180:183], s[22:23]
	v_lshlrev_b32_e32 v172, 16, v192
	v_and_b32_e32 v173, 0xffff0000, v192
	v_lshlrev_b32_e32 v174, 16, v193
	v_and_b32_e32 v175, 0xffff0000, v193
	v_lshlrev_b32_e32 v176, 16, v194
	v_and_b32_e32 v177, 0xffff0000, v194
	v_lshlrev_b32_e32 v178, 16, v195
	v_and_b32_e32 v179, 0xffff0000, v195
	v_mul_f32_e32 v120, v120, v128
	v_mul_f32_e32 v121, v121, v128
	v_mul_f32_e32 v122, v122, v128
	v_mul_f32_e32 v123, v123, v128
	v_mul_f32_e32 v116, v116, v128
	v_mul_f32_e32 v117, v117, v128
	v_mul_f32_e32 v118, v118, v128
	v_mul_f32_e32 v119, v119, v128
	v_fmac_f32_e32 v172, v120, v156
	v_fmac_f32_e32 v173, v121, v157
	v_fmac_f32_e32 v174, v122, v158
	v_fmac_f32_e32 v175, v123, v159
	v_fmac_f32_e32 v176, v116, v160
	v_fmac_f32_e32 v177, v117, v161
	v_fmac_f32_e32 v178, v118, v162
	v_fmac_f32_e32 v179, v119, v163
	v_fmac_f32_e32 v138, v172, v172
	v_fmac_f32_e32 v138, v173, v173
	v_fmac_f32_e32 v138, v174, v174
	v_fmac_f32_e32 v138, v175, v175
	v_fmac_f32_e32 v138, v176, v176
	v_fmac_f32_e32 v138, v177, v177
	v_fmac_f32_e32 v138, v178, v178
	v_fmac_f32_e32 v138, v179, v179
	v_cvt_pk_bf16_f32 v184, v172, v173
	v_cvt_pk_bf16_f32 v185, v174, v175
	v_cvt_pk_bf16_f32 v186, v176, v177
	v_cvt_pk_bf16_f32 v187, v178, v179
	global_store_dwordx4 v140, v[184:187], s[22:23] offset:256
	s_add_u32 s22, s60, 0x8000
	s_addc_u32 s23, s61, 0
	v_lshlrev_b32_e32 v164, 16, v196
	v_and_b32_e32 v165, 0xffff0000, v196
	v_lshlrev_b32_e32 v166, 16, v197
	v_and_b32_e32 v167, 0xffff0000, v197
	v_lshlrev_b32_e32 v168, 16, v198
	v_and_b32_e32 v169, 0xffff0000, v198
	v_lshlrev_b32_e32 v170, 16, v199
	v_and_b32_e32 v171, 0xffff0000, v199
	v_mul_f32_e32 v108, v108, v129
	v_mul_f32_e32 v109, v109, v129
	v_mul_f32_e32 v110, v110, v129
	v_mul_f32_e32 v111, v111, v129
	v_mul_f32_e32 v96, v96, v129
	v_mul_f32_e32 v97, v97, v129
	v_mul_f32_e32 v98, v98, v129
	v_mul_f32_e32 v99, v99, v129
	v_fmac_f32_e32 v164, v108, v148
	v_fmac_f32_e32 v165, v109, v149
	v_fmac_f32_e32 v166, v110, v150
	v_fmac_f32_e32 v167, v111, v151
	v_fmac_f32_e32 v168, v96, v152
	v_fmac_f32_e32 v169, v97, v153
	v_fmac_f32_e32 v170, v98, v154
	v_fmac_f32_e32 v171, v99, v155
	v_mul_f32_e32 v139, v164, v164
	v_fmac_f32_e32 v139, v165, v165
	v_fmac_f32_e32 v139, v166, v166
	v_fmac_f32_e32 v139, v167, v167
	v_fmac_f32_e32 v139, v168, v168
	v_fmac_f32_e32 v139, v169, v169
	v_fmac_f32_e32 v139, v170, v170
	v_fmac_f32_e32 v139, v171, v171
	v_cvt_pk_bf16_f32 v180, v164, v165
	v_cvt_pk_bf16_f32 v181, v166, v167
	v_cvt_pk_bf16_f32 v182, v168, v169
	v_cvt_pk_bf16_f32 v183, v170, v171
	global_store_dwordx4 v140, v[180:183], s[22:23]
	v_lshlrev_b32_e32 v172, 16, v200
	v_and_b32_e32 v173, 0xffff0000, v200
	v_lshlrev_b32_e32 v174, 16, v201
	v_and_b32_e32 v175, 0xffff0000, v201
	v_lshlrev_b32_e32 v176, 16, v202
	v_and_b32_e32 v177, 0xffff0000, v202
	v_lshlrev_b32_e32 v178, 16, v203
	v_and_b32_e32 v179, 0xffff0000, v203
	v_mul_f32_e32 v100, v100, v129
	v_mul_f32_e32 v101, v101, v129
	v_mul_f32_e32 v102, v102, v129
	v_mul_f32_e32 v103, v103, v129
	v_mul_f32_e32 v104, v104, v129
	v_mul_f32_e32 v105, v105, v129
	v_mul_f32_e32 v106, v106, v129
	v_mul_f32_e32 v107, v107, v129
	v_fmac_f32_e32 v172, v100, v156
	v_fmac_f32_e32 v173, v101, v157
	v_fmac_f32_e32 v174, v102, v158
	v_fmac_f32_e32 v175, v103, v159
	v_fmac_f32_e32 v176, v104, v160
	v_fmac_f32_e32 v177, v105, v161
	v_fmac_f32_e32 v178, v106, v162
	v_fmac_f32_e32 v179, v107, v163
	v_fmac_f32_e32 v139, v172, v172
	v_fmac_f32_e32 v139, v173, v173
	v_fmac_f32_e32 v139, v174, v174
	v_fmac_f32_e32 v139, v175, v175
	v_fmac_f32_e32 v139, v176, v176
	v_fmac_f32_e32 v139, v177, v177
	v_fmac_f32_e32 v139, v178, v178
	v_fmac_f32_e32 v139, v179, v179
	v_cvt_pk_bf16_f32 v184, v172, v173
	v_cvt_pk_bf16_f32 v185, v174, v175
	v_cvt_pk_bf16_f32 v186, v176, v177
	v_cvt_pk_bf16_f32 v187, v178, v179
	global_store_dwordx4 v140, v[184:187], s[22:23] offset:256
	s_add_u32 s22, s60, 0x10000
	s_addc_u32 s23, s61, 0
	v_lshlrev_b32_e32 v164, 16, v204
	v_and_b32_e32 v165, 0xffff0000, v204
	v_lshlrev_b32_e32 v166, 16, v205
	v_and_b32_e32 v167, 0xffff0000, v205
	v_lshlrev_b32_e32 v168, 16, v206
	v_and_b32_e32 v169, 0xffff0000, v206
	v_lshlrev_b32_e32 v170, 16, v207
	v_and_b32_e32 v171, 0xffff0000, v207
	v_mul_f32_e32 v92, v92, v130
	v_mul_f32_e32 v93, v93, v130
	v_mul_f32_e32 v94, v94, v130
	v_mul_f32_e32 v95, v95, v130
	v_mul_f32_e32 v80, v80, v130
	v_mul_f32_e32 v81, v81, v130
	v_mul_f32_e32 v82, v82, v130
	v_mul_f32_e32 v83, v83, v130
	v_fmac_f32_e32 v164, v92, v148
	v_fmac_f32_e32 v165, v93, v149
	v_fmac_f32_e32 v166, v94, v150
	v_fmac_f32_e32 v167, v95, v151
	v_fmac_f32_e32 v168, v80, v152
	v_fmac_f32_e32 v169, v81, v153
	v_fmac_f32_e32 v170, v82, v154
	v_fmac_f32_e32 v171, v83, v155
	v_mul_f32_e32 v141, v164, v164
	v_fmac_f32_e32 v141, v165, v165
	v_fmac_f32_e32 v141, v166, v166
	v_fmac_f32_e32 v141, v167, v167
	v_fmac_f32_e32 v141, v168, v168
	v_fmac_f32_e32 v141, v169, v169
	v_fmac_f32_e32 v141, v170, v170
	v_fmac_f32_e32 v141, v171, v171
	v_cvt_pk_bf16_f32 v180, v164, v165
	v_cvt_pk_bf16_f32 v181, v166, v167
	v_cvt_pk_bf16_f32 v182, v168, v169
	v_cvt_pk_bf16_f32 v183, v170, v171
	global_store_dwordx4 v140, v[180:183], s[22:23]
	v_lshlrev_b32_e32 v172, 16, v208
	v_and_b32_e32 v173, 0xffff0000, v208
	v_lshlrev_b32_e32 v174, 16, v209
	v_and_b32_e32 v175, 0xffff0000, v209
	v_lshlrev_b32_e32 v176, 16, v210
	v_and_b32_e32 v177, 0xffff0000, v210
	v_lshlrev_b32_e32 v178, 16, v211
	v_and_b32_e32 v179, 0xffff0000, v211
	v_mul_f32_e32 v84, v84, v130
	v_mul_f32_e32 v85, v85, v130
	v_mul_f32_e32 v86, v86, v130
	v_mul_f32_e32 v87, v87, v130
	v_mul_f32_e32 v88, v88, v130
	v_mul_f32_e32 v89, v89, v130
	v_mul_f32_e32 v90, v90, v130
	v_mul_f32_e32 v91, v91, v130
	v_fmac_f32_e32 v172, v84, v156
	v_fmac_f32_e32 v173, v85, v157
	v_fmac_f32_e32 v174, v86, v158
	v_fmac_f32_e32 v175, v87, v159
	v_fmac_f32_e32 v176, v88, v160
	v_fmac_f32_e32 v177, v89, v161
	v_fmac_f32_e32 v178, v90, v162
	v_fmac_f32_e32 v179, v91, v163
	v_fmac_f32_e32 v141, v172, v172
	v_fmac_f32_e32 v141, v173, v173
	v_fmac_f32_e32 v141, v174, v174
	v_fmac_f32_e32 v141, v175, v175
	v_fmac_f32_e32 v141, v176, v176
	v_fmac_f32_e32 v141, v177, v177
	v_fmac_f32_e32 v141, v178, v178
	v_fmac_f32_e32 v141, v179, v179
	v_cvt_pk_bf16_f32 v184, v172, v173
	v_cvt_pk_bf16_f32 v185, v174, v175
	v_cvt_pk_bf16_f32 v186, v176, v177
	v_cvt_pk_bf16_f32 v187, v178, v179
	global_store_dwordx4 v140, v[184:187], s[22:23] offset:256
	s_add_u32 s22, s60, 0x18000
	s_addc_u32 s23, s61, 0
	v_lshlrev_b32_e32 v164, 16, v212
	v_and_b32_e32 v165, 0xffff0000, v212
	v_lshlrev_b32_e32 v166, 16, v213
	v_and_b32_e32 v167, 0xffff0000, v213
	v_lshlrev_b32_e32 v168, 16, v214
	v_and_b32_e32 v169, 0xffff0000, v214
	v_lshlrev_b32_e32 v170, 16, v215
	v_and_b32_e32 v171, 0xffff0000, v215
	v_mul_f32_e32 v76, v76, v131
	v_mul_f32_e32 v77, v77, v131
	v_mul_f32_e32 v78, v78, v131
	v_mul_f32_e32 v79, v79, v131
	v_mul_f32_e32 v64, v64, v131
	v_mul_f32_e32 v65, v65, v131
	v_mul_f32_e32 v66, v66, v131
	v_mul_f32_e32 v67, v67, v131
	v_fmac_f32_e32 v164, v76, v148
	v_fmac_f32_e32 v165, v77, v149
	v_fmac_f32_e32 v166, v78, v150
	v_fmac_f32_e32 v167, v79, v151
	v_fmac_f32_e32 v168, v64, v152
	v_fmac_f32_e32 v169, v65, v153
	v_fmac_f32_e32 v170, v66, v154
	v_fmac_f32_e32 v171, v67, v155
	v_mul_f32_e32 v142, v164, v164
	v_fmac_f32_e32 v142, v165, v165
	v_fmac_f32_e32 v142, v166, v166
	v_fmac_f32_e32 v142, v167, v167
	v_fmac_f32_e32 v142, v168, v168
	v_fmac_f32_e32 v142, v169, v169
	v_fmac_f32_e32 v142, v170, v170
	v_fmac_f32_e32 v142, v171, v171
	v_cvt_pk_bf16_f32 v180, v164, v165
	v_cvt_pk_bf16_f32 v181, v166, v167
	v_cvt_pk_bf16_f32 v182, v168, v169
	v_cvt_pk_bf16_f32 v183, v170, v171
	global_store_dwordx4 v140, v[180:183], s[22:23]
	v_lshlrev_b32_e32 v172, 16, v216
	v_and_b32_e32 v173, 0xffff0000, v216
	v_lshlrev_b32_e32 v174, 16, v217
	v_and_b32_e32 v175, 0xffff0000, v217
	v_lshlrev_b32_e32 v176, 16, v218
	v_and_b32_e32 v177, 0xffff0000, v218
	v_lshlrev_b32_e32 v178, 16, v219
	v_and_b32_e32 v179, 0xffff0000, v219
	v_mul_f32_e32 v68, v68, v131
	v_mul_f32_e32 v69, v69, v131
	v_mul_f32_e32 v70, v70, v131
	v_mul_f32_e32 v71, v71, v131
	v_mul_f32_e32 v72, v72, v131
	v_mul_f32_e32 v73, v73, v131
	v_mul_f32_e32 v74, v74, v131
	v_mul_f32_e32 v75, v75, v131
	v_fmac_f32_e32 v172, v68, v156
	v_fmac_f32_e32 v173, v69, v157
	v_fmac_f32_e32 v174, v70, v158
	v_fmac_f32_e32 v175, v71, v159
	v_fmac_f32_e32 v176, v72, v160
	v_fmac_f32_e32 v177, v73, v161
	v_fmac_f32_e32 v178, v74, v162
	v_fmac_f32_e32 v179, v75, v163
	v_fmac_f32_e32 v142, v172, v172
	v_fmac_f32_e32 v142, v173, v173
	v_fmac_f32_e32 v142, v174, v174
	v_fmac_f32_e32 v142, v175, v175
	v_fmac_f32_e32 v142, v176, v176
	v_fmac_f32_e32 v142, v177, v177
	v_fmac_f32_e32 v142, v178, v178
	v_fmac_f32_e32 v142, v179, v179
	v_cvt_pk_bf16_f32 v184, v172, v173
	v_cvt_pk_bf16_f32 v185, v174, v175
	v_cvt_pk_bf16_f32 v186, v176, v177
	v_cvt_pk_bf16_f32 v187, v178, v179
	global_store_dwordx4 v140, v[184:187], s[22:23] offset:256
	s_add_u32 s22, s60, 0x40000
	s_addc_u32 s23, s61, 0
	v_lshlrev_b32_e32 v164, 16, v220
	v_and_b32_e32 v165, 0xffff0000, v220
	v_lshlrev_b32_e32 v166, 16, v221
	v_and_b32_e32 v167, 0xffff0000, v221
	v_lshlrev_b32_e32 v168, 16, v222
	v_and_b32_e32 v169, 0xffff0000, v222
	v_lshlrev_b32_e32 v170, 16, v223
	v_and_b32_e32 v171, 0xffff0000, v223
	v_mul_f32_e32 v60, v60, v132
	v_mul_f32_e32 v61, v61, v132
	v_mul_f32_e32 v62, v62, v132
	v_mul_f32_e32 v63, v63, v132
	v_mul_f32_e32 v48, v48, v132
	v_mul_f32_e32 v49, v49, v132
	v_mul_f32_e32 v50, v50, v132
	v_mul_f32_e32 v51, v51, v132
	v_fmac_f32_e32 v164, v60, v148
	v_fmac_f32_e32 v165, v61, v149
	v_fmac_f32_e32 v166, v62, v150
	v_fmac_f32_e32 v167, v63, v151
	v_fmac_f32_e32 v168, v48, v152
	v_fmac_f32_e32 v169, v49, v153
	v_fmac_f32_e32 v170, v50, v154
	v_fmac_f32_e32 v171, v51, v155
	v_mul_f32_e32 v143, v164, v164
	v_fmac_f32_e32 v143, v165, v165
	v_fmac_f32_e32 v143, v166, v166
	v_fmac_f32_e32 v143, v167, v167
	v_fmac_f32_e32 v143, v168, v168
	v_fmac_f32_e32 v143, v169, v169
	v_fmac_f32_e32 v143, v170, v170
	v_fmac_f32_e32 v143, v171, v171
	v_cvt_pk_bf16_f32 v180, v164, v165
	v_cvt_pk_bf16_f32 v181, v166, v167
	v_cvt_pk_bf16_f32 v182, v168, v169
	v_cvt_pk_bf16_f32 v183, v170, v171
	global_store_dwordx4 v140, v[180:183], s[22:23]
	v_lshlrev_b32_e32 v172, 16, v224
	v_and_b32_e32 v173, 0xffff0000, v224
	v_lshlrev_b32_e32 v174, 16, v225
	v_and_b32_e32 v175, 0xffff0000, v225
	v_lshlrev_b32_e32 v176, 16, v226
	v_and_b32_e32 v177, 0xffff0000, v226
	v_lshlrev_b32_e32 v178, 16, v227
	v_and_b32_e32 v179, 0xffff0000, v227
	v_mul_f32_e32 v52, v52, v132
	v_mul_f32_e32 v53, v53, v132
	v_mul_f32_e32 v54, v54, v132
	v_mul_f32_e32 v55, v55, v132
	v_mul_f32_e32 v56, v56, v132
	v_mul_f32_e32 v57, v57, v132
	v_mul_f32_e32 v58, v58, v132
	v_mul_f32_e32 v59, v59, v132
	v_fmac_f32_e32 v172, v52, v156
	v_fmac_f32_e32 v173, v53, v157
	v_fmac_f32_e32 v174, v54, v158
	v_fmac_f32_e32 v175, v55, v159
	v_fmac_f32_e32 v176, v56, v160
	v_fmac_f32_e32 v177, v57, v161
	v_fmac_f32_e32 v178, v58, v162
	v_fmac_f32_e32 v179, v59, v163
	v_fmac_f32_e32 v143, v172, v172
	v_fmac_f32_e32 v143, v173, v173
	v_fmac_f32_e32 v143, v174, v174
	v_fmac_f32_e32 v143, v175, v175
	v_fmac_f32_e32 v143, v176, v176
	v_fmac_f32_e32 v143, v177, v177
	v_fmac_f32_e32 v143, v178, v178
	v_fmac_f32_e32 v143, v179, v179
	v_cvt_pk_bf16_f32 v184, v172, v173
	v_cvt_pk_bf16_f32 v185, v174, v175
	v_cvt_pk_bf16_f32 v186, v176, v177
	v_cvt_pk_bf16_f32 v187, v178, v179
	global_store_dwordx4 v140, v[184:187], s[22:23] offset:256
	s_add_u32 s22, s60, 0x48000
	s_addc_u32 s23, s61, 0
	v_lshlrev_b32_e32 v164, 16, v228
	v_and_b32_e32 v165, 0xffff0000, v228
	v_lshlrev_b32_e32 v166, 16, v229
	v_and_b32_e32 v167, 0xffff0000, v229
	v_lshlrev_b32_e32 v168, 16, v230
	v_and_b32_e32 v169, 0xffff0000, v230
	v_lshlrev_b32_e32 v170, 16, v231
	v_and_b32_e32 v171, 0xffff0000, v231
	v_mul_f32_e32 v44, v44, v133
	v_mul_f32_e32 v45, v45, v133
	v_mul_f32_e32 v46, v46, v133
	v_mul_f32_e32 v47, v47, v133
	v_mul_f32_e32 v32, v32, v133
	v_mul_f32_e32 v33, v33, v133
	v_mul_f32_e32 v34, v34, v133
	v_mul_f32_e32 v35, v35, v133
	v_fmac_f32_e32 v164, v44, v148
	v_fmac_f32_e32 v165, v45, v149
	v_fmac_f32_e32 v166, v46, v150
	v_fmac_f32_e32 v167, v47, v151
	v_fmac_f32_e32 v168, v32, v152
	v_fmac_f32_e32 v169, v33, v153
	v_fmac_f32_e32 v170, v34, v154
	v_fmac_f32_e32 v171, v35, v155
	v_mul_f32_e32 v144, v164, v164
	v_fmac_f32_e32 v144, v165, v165
	v_fmac_f32_e32 v144, v166, v166
	v_fmac_f32_e32 v144, v167, v167
	v_fmac_f32_e32 v144, v168, v168
	v_fmac_f32_e32 v144, v169, v169
	v_fmac_f32_e32 v144, v170, v170
	v_fmac_f32_e32 v144, v171, v171
	v_cvt_pk_bf16_f32 v180, v164, v165
	v_cvt_pk_bf16_f32 v181, v166, v167
	v_cvt_pk_bf16_f32 v182, v168, v169
	v_cvt_pk_bf16_f32 v183, v170, v171
	global_store_dwordx4 v140, v[180:183], s[22:23]
	v_lshlrev_b32_e32 v172, 16, v232
	v_and_b32_e32 v173, 0xffff0000, v232
	v_lshlrev_b32_e32 v174, 16, v233
	v_and_b32_e32 v175, 0xffff0000, v233
	v_lshlrev_b32_e32 v176, 16, v234
	v_and_b32_e32 v177, 0xffff0000, v234
	v_lshlrev_b32_e32 v178, 16, v235
	v_and_b32_e32 v179, 0xffff0000, v235
	v_mul_f32_e32 v36, v36, v133
	v_mul_f32_e32 v37, v37, v133
	v_mul_f32_e32 v38, v38, v133
	v_mul_f32_e32 v39, v39, v133
	v_mul_f32_e32 v40, v40, v133
	v_mul_f32_e32 v41, v41, v133
	v_mul_f32_e32 v42, v42, v133
	v_mul_f32_e32 v43, v43, v133
	v_fmac_f32_e32 v172, v36, v156
	v_fmac_f32_e32 v173, v37, v157
	v_fmac_f32_e32 v174, v38, v158
	v_fmac_f32_e32 v175, v39, v159
	v_fmac_f32_e32 v176, v40, v160
	v_fmac_f32_e32 v177, v41, v161
	v_fmac_f32_e32 v178, v42, v162
	v_fmac_f32_e32 v179, v43, v163
	v_fmac_f32_e32 v144, v172, v172
	v_fmac_f32_e32 v144, v173, v173
	v_fmac_f32_e32 v144, v174, v174
	v_fmac_f32_e32 v144, v175, v175
	v_fmac_f32_e32 v144, v176, v176
	v_fmac_f32_e32 v144, v177, v177
	v_fmac_f32_e32 v144, v178, v178
	v_fmac_f32_e32 v144, v179, v179
	v_cvt_pk_bf16_f32 v184, v172, v173
	v_cvt_pk_bf16_f32 v185, v174, v175
	v_cvt_pk_bf16_f32 v186, v176, v177
	v_cvt_pk_bf16_f32 v187, v178, v179
	global_store_dwordx4 v140, v[184:187], s[22:23] offset:256
	s_add_u32 s22, s60, 0x50000
	s_addc_u32 s23, s61, 0
	v_lshlrev_b32_e32 v164, 16, v236
	v_and_b32_e32 v165, 0xffff0000, v236
	v_lshlrev_b32_e32 v166, 16, v237
	v_and_b32_e32 v167, 0xffff0000, v237
	v_lshlrev_b32_e32 v168, 16, v238
	v_and_b32_e32 v169, 0xffff0000, v238
	v_lshlrev_b32_e32 v170, 16, v239
	v_and_b32_e32 v171, 0xffff0000, v239
	v_mul_f32_e32 v28, v28, v134
	v_mul_f32_e32 v29, v29, v134
	v_mul_f32_e32 v30, v30, v134
	v_mul_f32_e32 v31, v31, v134
	v_mul_f32_e32 v16, v16, v134
	v_mul_f32_e32 v17, v17, v134
	v_mul_f32_e32 v18, v18, v134
	v_mul_f32_e32 v19, v19, v134
	v_fmac_f32_e32 v164, v28, v148
	v_fmac_f32_e32 v165, v29, v149
	v_fmac_f32_e32 v166, v30, v150
	v_fmac_f32_e32 v167, v31, v151
	v_fmac_f32_e32 v168, v16, v152
	v_fmac_f32_e32 v169, v17, v153
	v_fmac_f32_e32 v170, v18, v154
	v_fmac_f32_e32 v171, v19, v155
	v_mul_f32_e32 v145, v164, v164
	v_fmac_f32_e32 v145, v165, v165
	v_fmac_f32_e32 v145, v166, v166
	v_fmac_f32_e32 v145, v167, v167
	v_fmac_f32_e32 v145, v168, v168
	v_fmac_f32_e32 v145, v169, v169
	v_fmac_f32_e32 v145, v170, v170
	v_fmac_f32_e32 v145, v171, v171
	v_cvt_pk_bf16_f32 v180, v164, v165
	v_cvt_pk_bf16_f32 v181, v166, v167
	v_cvt_pk_bf16_f32 v182, v168, v169
	v_cvt_pk_bf16_f32 v183, v170, v171
	global_store_dwordx4 v140, v[180:183], s[22:23]
	v_lshlrev_b32_e32 v172, 16, v240
	v_and_b32_e32 v173, 0xffff0000, v240
	v_lshlrev_b32_e32 v174, 16, v241
	v_and_b32_e32 v175, 0xffff0000, v241
	v_lshlrev_b32_e32 v176, 16, v242
	v_and_b32_e32 v177, 0xffff0000, v242
	v_lshlrev_b32_e32 v178, 16, v243
	v_and_b32_e32 v179, 0xffff0000, v243
	v_mul_f32_e32 v20, v20, v134
	v_mul_f32_e32 v21, v21, v134
	v_mul_f32_e32 v22, v22, v134
	v_mul_f32_e32 v23, v23, v134
	v_mul_f32_e32 v24, v24, v134
	v_mul_f32_e32 v25, v25, v134
	v_mul_f32_e32 v26, v26, v134
	v_mul_f32_e32 v27, v27, v134
	v_fmac_f32_e32 v172, v20, v156
	v_fmac_f32_e32 v173, v21, v157
	v_fmac_f32_e32 v174, v22, v158
	v_fmac_f32_e32 v175, v23, v159
	v_fmac_f32_e32 v176, v24, v160
	v_fmac_f32_e32 v177, v25, v161
	v_fmac_f32_e32 v178, v26, v162
	v_fmac_f32_e32 v179, v27, v163
	v_fmac_f32_e32 v145, v172, v172
	v_fmac_f32_e32 v145, v173, v173
	v_fmac_f32_e32 v145, v174, v174
	v_fmac_f32_e32 v145, v175, v175
	v_fmac_f32_e32 v145, v176, v176
	v_fmac_f32_e32 v145, v177, v177
	v_fmac_f32_e32 v145, v178, v178
	v_fmac_f32_e32 v145, v179, v179
	v_cvt_pk_bf16_f32 v184, v172, v173
	v_cvt_pk_bf16_f32 v185, v174, v175
	v_cvt_pk_bf16_f32 v186, v176, v177
	v_cvt_pk_bf16_f32 v187, v178, v179
	global_store_dwordx4 v140, v[184:187], s[22:23] offset:256
	s_add_u32 s22, s60, 0x58000
	s_addc_u32 s23, s61, 0
	v_lshlrev_b32_e32 v164, 16, v244
	v_and_b32_e32 v165, 0xffff0000, v244
	v_lshlrev_b32_e32 v166, 16, v245
	v_and_b32_e32 v167, 0xffff0000, v245
	v_lshlrev_b32_e32 v168, 16, v246
	v_and_b32_e32 v169, 0xffff0000, v246
	v_lshlrev_b32_e32 v170, 16, v247
	v_and_b32_e32 v171, 0xffff0000, v247
	v_mul_f32_e32 v12, v12, v135
	v_mul_f32_e32 v13, v13, v135
	v_mul_f32_e32 v14, v14, v135
	v_mul_f32_e32 v15, v15, v135
	v_mul_f32_e32 v0, v0, v135
	v_mul_f32_e32 v1, v1, v135
	v_mul_f32_e32 v2, v2, v135
	v_mul_f32_e32 v3, v3, v135
	v_fmac_f32_e32 v164, v12, v148
	v_fmac_f32_e32 v165, v13, v149
	v_fmac_f32_e32 v166, v14, v150
	v_fmac_f32_e32 v167, v15, v151
	v_fmac_f32_e32 v168, v0, v152
	v_fmac_f32_e32 v169, v1, v153
	v_fmac_f32_e32 v170, v2, v154
	v_fmac_f32_e32 v171, v3, v155
	v_mul_f32_e32 v146, v164, v164
	v_fmac_f32_e32 v146, v165, v165
	v_fmac_f32_e32 v146, v166, v166
	v_fmac_f32_e32 v146, v167, v167
	v_fmac_f32_e32 v146, v168, v168
	v_fmac_f32_e32 v146, v169, v169
	v_fmac_f32_e32 v146, v170, v170
	v_fmac_f32_e32 v146, v171, v171
	v_cvt_pk_bf16_f32 v180, v164, v165
	v_cvt_pk_bf16_f32 v181, v166, v167
	v_cvt_pk_bf16_f32 v182, v168, v169
	v_cvt_pk_bf16_f32 v183, v170, v171
	global_store_dwordx4 v140, v[180:183], s[22:23]
	v_lshlrev_b32_e32 v172, 16, v248
	v_and_b32_e32 v173, 0xffff0000, v248
	v_lshlrev_b32_e32 v174, 16, v249
	v_and_b32_e32 v175, 0xffff0000, v249
	v_lshlrev_b32_e32 v176, 16, v250
	v_and_b32_e32 v177, 0xffff0000, v250
	v_lshlrev_b32_e32 v178, 16, v251
	v_and_b32_e32 v179, 0xffff0000, v251
	v_mul_f32_e32 v4, v4, v135
	v_mul_f32_e32 v5, v5, v135
	v_mul_f32_e32 v6, v6, v135
	v_mul_f32_e32 v7, v7, v135
	v_mul_f32_e32 v8, v8, v135
	v_mul_f32_e32 v9, v9, v135
	v_mul_f32_e32 v10, v10, v135
	v_mul_f32_e32 v11, v11, v135
	v_fmac_f32_e32 v172, v4, v156
	v_fmac_f32_e32 v173, v5, v157
	v_fmac_f32_e32 v174, v6, v158
	v_fmac_f32_e32 v175, v7, v159
	v_fmac_f32_e32 v176, v8, v160
	v_fmac_f32_e32 v177, v9, v161
	v_fmac_f32_e32 v178, v10, v162
	v_fmac_f32_e32 v179, v11, v163
	v_fmac_f32_e32 v146, v172, v172
	v_fmac_f32_e32 v146, v173, v173
	v_fmac_f32_e32 v146, v174, v174
	v_fmac_f32_e32 v146, v175, v175
	v_fmac_f32_e32 v146, v176, v176
	v_fmac_f32_e32 v146, v177, v177
	v_fmac_f32_e32 v146, v178, v178
	v_fmac_f32_e32 v146, v179, v179
	v_cvt_pk_bf16_f32 v184, v172, v173
	v_cvt_pk_bf16_f32 v185, v174, v175
	v_cvt_pk_bf16_f32 v186, v176, v177
	v_cvt_pk_bf16_f32 v187, v178, v179
	global_store_dwordx4 v140, v[184:187], s[22:23] offset:256
	v_mov_b32_e32 v148, v138
	v_mov_b32_e32 v149, v139
	v_mov_b32_e32 v150, v141
	v_mov_b32_e32 v151, v142
	v_mov_b32_e32 v152, v143
	v_mov_b32_e32 v153, v144
	v_mov_b32_e32 v154, v145
	v_mov_b32_e32 v155, v146
	v_xor_b32_e32 v138, 16, v137
	v_xor_b32_e32 v139, 32, v137
	v_lshlrev_b32_e32 v138, 2, v138
	v_lshlrev_b32_e32 v139, 2, v139
	ds_bpermute_b32 v164, v138, v148
	ds_bpermute_b32 v165, v138, v149
	ds_bpermute_b32 v166, v138, v150
	ds_bpermute_b32 v167, v138, v151
	ds_bpermute_b32 v168, v138, v152
	ds_bpermute_b32 v169, v138, v153
	ds_bpermute_b32 v170, v138, v154
	ds_bpermute_b32 v171, v138, v155
	s_waitcnt lgkmcnt(0)
	v_add_f32_e32 v148, v148, v164
	v_add_f32_e32 v149, v149, v165
	v_add_f32_e32 v150, v150, v166
	v_add_f32_e32 v151, v151, v167
	v_add_f32_e32 v152, v152, v168
	v_add_f32_e32 v153, v153, v169
	v_add_f32_e32 v154, v154, v170
	v_add_f32_e32 v155, v155, v171
	ds_bpermute_b32 v164, v139, v148
	ds_bpermute_b32 v165, v139, v149
	ds_bpermute_b32 v166, v139, v150
	ds_bpermute_b32 v167, v139, v151
	ds_bpermute_b32 v168, v139, v152
	ds_bpermute_b32 v169, v139, v153
	ds_bpermute_b32 v170, v139, v154
	ds_bpermute_b32 v171, v139, v155
	s_waitcnt lgkmcnt(0)
	v_add_f32_e32 v148, v148, v164
	v_add_f32_e32 v149, v149, v165
	v_add_f32_e32 v150, v150, v166
	v_add_f32_e32 v151, v151, v167
	v_add_f32_e32 v152, v152, v168
	v_add_f32_e32 v153, v153, v169
	v_add_f32_e32 v154, v154, v170
	v_add_f32_e32 v155, v155, v171
	s_and_b32 s98, s2, 7
	s_lshl_b32 s98, s98, 3
	s_bfe_u32 s99, s2, 0x30003
	s_or_b32 s98, s98, s99
	s_lshr_b32 s99, s2, 6
	s_mul_i32 s99, s99, 0x42000
	s_lshl_b32 s98, s98, 10
	s_add_u32 s100, s56, s99
	s_addc_u32 s101, s57, 0
	s_add_u32 s100, s100, s98
	s_addc_u32 s101, s101, 0
	v_lshrrev_b32_e32 v158, 8, v136
	v_bfe_u32 v159, v136, 6, 2
	v_and_b32_e32 v160, 15, v136
	v_lshl_add_u32 v160, v158, 6, v160
	v_mul_u32_u24_e32 v159, 0x4200, v159
	v_add_u32_e32 v160, v160, v159
	v_lshlrev_b32_e32 v160, 2, v160
	v_bfe_u32 v161, v136, 4, 2
	v_cmp_eq_u32_e32 vcc, 0, v161
	s_and_saveexec_b64 s[0:1], vcc
	global_store_dword v160, v148, s[100:101]
	global_store_dword v160, v149, s[100:101] offset:64
	global_store_dword v160, v150, s[100:101] offset:128
	global_store_dword v160, v151, s[100:101] offset:192
	global_store_dword v160, v152, s[100:101] offset:512
	global_store_dword v160, v153, s[100:101] offset:576
	global_store_dword v160, v154, s[100:101] offset:640
	global_store_dword v160, v155, s[100:101] offset:704
	s_or_b64 exec, exec, s[0:1]
	v_bfe_u32 v183, v136, 1, 2
	v_lshrrev_b32_e32 v187, 6, v136
	v_lshlrev_b32_e32 v190, 11, v136
	v_lshrrev_b32_e32 v252, 1, v136
	v_and_b32_e32 v132, 48, v136
	v_and_b32_e32 v189, 63, v136
	v_lshrrev_b32_e32 v182, 3, v136
	v_lshlrev_b32_e32 v188, 2, v136
	v_lshl_add_u32 v186, v183, 6, 0
	v_and_b32_e32 v191, 15, v136
	s_cmpk_lt_i32 s2, 0x420
	v_mov_b32_e32 v0, v136
	s_cselect_b64 s[8:9], -1, 0
	s_cmpk_gt_i32 s2, 0x41f
	s_cbranch_scc1 .LBB0_863
	v_and_b32_e32 v4, 63, v0
	v_ashrrev_i32_e32 v0, 5, v0
	v_readlane_b32 s12, v253, 3
	v_and_b32_e32 v5, -2, v0
	v_lshlrev_b32_e32 v0, 4, v4
	v_mov_b32_e32 v1, 0
	v_readlane_b32 s13, v253, 4
	s_mov_b64 s[0:1], 0x1000
	v_readlane_b32 s14, v253, 5
	v_lshl_add_u64 v[2:3], s[12:13], 0, v[0:1]
	v_lshl_add_u64 v[16:17], v[2:3], 0, s[0:1]
	v_and_b32_e32 v2, 64, v137
	v_add_u32_e32 v2, 64, v2
	v_xor_b32_e32 v3, 32, v137
	v_cmp_lt_i32_e64 s[0:1], v3, v2
	v_readlane_b32 s15, v253, 6
	v_readlane_b32 s16, v253, 7
	v_cndmask_b32_e64 v3, v137, v3, s[0:1]
	v_lshlrev_b32_e32 v50, 2, v3
	v_xor_b32_e32 v3, 16, v137
	v_cmp_lt_i32_e64 s[0:1], v3, v2
	v_readlane_b32 s17, v253, 8
	v_readlane_b32 s18, v253, 9
	v_cndmask_b32_e64 v3, v137, v3, s[0:1]
	v_lshlrev_b32_e32 v51, 2, v3
	v_xor_b32_e32 v3, 8, v137
	v_cmp_lt_i32_e64 s[0:1], v3, v2
	v_readlane_b32 s19, v253, 10
	v_readlane_b32 s20, v253, 11
	v_cndmask_b32_e64 v3, v137, v3, s[0:1]
	v_lshlrev_b32_e32 v52, 2, v3
	v_xor_b32_e32 v3, 4, v137
	v_cmp_lt_i32_e64 s[0:1], v3, v2
	v_readlane_b32 s21, v253, 12
	v_readlane_b32 s22, v253, 13
	v_cndmask_b32_e64 v3, v137, v3, s[0:1]
	v_lshlrev_b32_e32 v53, 2, v3
	v_xor_b32_e32 v3, 2, v137
	v_cmp_lt_i32_e64 s[0:1], v3, v2
	v_readlane_b32 s23, v253, 14
	v_readlane_b32 s24, v253, 15
	v_cndmask_b32_e64 v3, v137, v3, s[0:1]
	v_readlane_b32 s25, v253, 16
	v_readlane_b32 s26, v253, 17
	v_readlane_b32 s27, v253, 18
	v_mul_u32_u24_e32 v0, 0x4200, v4
	v_lshlrev_b32_e32 v54, 2, v3
	v_xor_b32_e32 v3, 1, v137
	v_cmp_lt_i32_e64 s[0:1], v3, v2
	v_lshlrev_b32_e32 v0, 2, v0
	v_readlane_b32 s12, v253, 51
	v_cndmask_b32_e64 v2, v137, v3, s[0:1]
	v_lshl_add_u64 v[18:19], s[44:45], 0, v[0:1]
	v_lshlrev_b32_e32 v0, 3, v4
	v_readlane_b32 s13, v253, 52
	v_readlane_b32 s14, v253, 53
	v_readlane_b32 s15, v253, 54
	v_cmp_gt_u32_e32 vcc, 16, v4
	v_lshlrev_b32_e32 v55, 2, v2
	v_cmp_eq_u32_e64 s[0:1], 0, v4
	v_lshl_add_u64 v[20:21], s[60:61], 0, v[0:1]
	v_lshl_add_u64 v[22:23], s[14:15], 0, v[0:1]
	v_lshl_add_u64 v[24:25], s[58:59], 0, v[0:1]
	v_lshl_add_u32 v26, s2, 4, v5
	s_lshl_b32 s3, s38, 4
	v_mov_b32_e32 v56, 0x358637bd
	s_mov_b32 s12, 0x800000
	s_mov_b32 s13, s2
	v_readlane_b32 s16, v253, 55
	v_readlane_b32 s17, v253, 56
	v_readlane_b32 s18, v253, 57
	v_readlane_b32 s19, v253, 58
	v_readlane_b32 s20, v253, 59
	v_readlane_b32 s21, v253, 60
	v_readlane_b32 s22, v253, 61
	v_readlane_b32 s23, v253, 62
	v_readlane_b32 s24, v253, 63
	v_readlane_b32 s25, v254, 0
	v_readlane_b32 s26, v254, 1
	v_readlane_b32 s27, v254, 2
	s_addk_i32 s13, 0x400
	v_add_u32_e32 v26, 0x4000, v26
	s_cmpk_lt_i32 s13, 0x420
	s_cbranch_scc0 .LBB0_863
	s_branch .LBB0_855

.LBB0_915:
	s_or_b64 exec, exec, s[0:1]
	s_waitcnt lgkmcnt(0)
	v_cndmask_b32_e64 v0, 0, 1, s[10:11]
	v_cmp_ne_u32_e64 s[4:5], 1, v0
	s_andn2_b64 vcc, exec, s[10:11]
	s_barrier
	s_and_b32 s98, s2, 7
	s_lshl_b32 s98, s98, 3
	s_bfe_u32 s99, s2, 0x30003
	s_or_b32 s98, s98, s99
	s_lshr_b32 s99, s2, 6
	v_and_b32_e32 v140, 0xff, v136
	v_lshrrev_b32_e32 v141, 8, v136
	v_mul_u32_u24_e32 v141, 0x84000, v141
	v_lshl_add_u32 v140, v140, 2, v141
	s_lshl_b32 s24, s98, 10
	s_add_u32 s18, s56, s24
	s_addc_u32 s19, s57, 0
	global_load_dword v142, v140, s[18:19]
	s_add_u32 s18, s18, 0x10800
	s_addc_u32 s19, s19, 0
	global_load_dword v143, v140, s[18:19]
	s_add_u32 s18, s18, 0x10800
	s_addc_u32 s19, s19, 0
	global_load_dword v144, v140, s[18:19]
	s_add_u32 s18, s18, 0x10800
	s_addc_u32 s19, s19, 0
	global_load_dword v145, v140, s[18:19]
	s_add_u32 s18, s18, 0x10800
	s_addc_u32 s19, s19, 0
	global_load_dword v146, v140, s[18:19]
	s_add_u32 s18, s18, 0x10800
	s_addc_u32 s19, s19, 0
	global_load_dword v147, v140, s[18:19]
	s_add_u32 s18, s18, 0x10800
	s_addc_u32 s19, s19, 0
	global_load_dword v148, v140, s[18:19]
	s_add_u32 s18, s18, 0x10800
	s_addc_u32 s19, s19, 0
	global_load_dword v149, v140, s[18:19]
	s_waitcnt vmcnt(0)
	v_add_f32_e32 v142, v142, v143
	v_add_f32_e32 v142, v142, v144
	v_add_f32_e32 v142, v142, v145
	v_add_f32_e32 v142, v142, v146
	v_add_f32_e32 v142, v142, v147
	v_add_f32_e32 v142, v142, v148
	v_add_f32_e32 v142, v142, v149
	v_lshlrev_b32_e32 v141, 2, v136
	ds_write_b32 v141, v142 offset:0
	s_waitcnt lgkmcnt(0)
	s_barrier
	v_cmp_gt_u32_e32 vcc, 0x100, v136
	s_and_saveexec_b64 s[18:19], vcc
	ds_read_b32 v142, v141 offset:0
	ds_read_b32 v143, v141 offset:1024
	s_mov_b32 s25, 0x3a800000
	v_mov_b32_e32 v144, 0x358637bd
	s_waitcnt lgkmcnt(0)
	v_add_f32_e32 v142, v142, v143
	v_fma_f32 v142, v142, s25, v144
	v_rsq_f32_e32 v142, v142
	s_add_u32 s24, s46, s24
	s_addc_u32 s25, s47, 0
	s_nop 0
	global_store_dword v141, v142, s[24:25]
	s_or_b64 exec, exec, s[18:19]
	s_waitcnt vmcnt(0)
	s_barrier
	s_andn2_b64 vcc, exec, s[10:11]
	s_cbranch_vccnz .LBB0_920
	v_readlane_b32 s12, v253, 51
	v_and_b32_e32 v0, 0x7800, v190
	v_mov_b32_e32 v1, 0
	v_readlane_b32 s26, v254, 1
	v_readlane_b32 s27, v254, 2
	v_mov_b32_e32 v133, v1
	v_and_b32_e32 v7, 4, v188
	v_lshl_add_u64 v[2:3], s[26:27], 0, v[0:1]
	v_lshl_add_u64 v[4:5], v[2:3], 0, v[132:133]
	v_lshl_add_u64 v[2:3], s[60:61], 0, v[0:1]
	v_lshl_add_u64 v[2:3], v[2:3], 0, v[132:133]
	v_lshlrev_b32_e32 v0, 8, v187
	v_and_or_b32 v6, v182, 16, v7
	v_readlane_b32 s14, v253, 53
	v_readlane_b32 s15, v253, 54
	v_readlane_b32 s16, v253, 55
	v_readlane_b32 s17, v253, 56
	v_readlane_b32 s18, v253, 57
	v_readlane_b32 s19, v253, 58
	v_readlane_b32 s20, v253, 59
	v_readlane_b32 s21, v253, 60
	v_readlane_b32 s22, v253, 61
	v_lshl_add_u64 v[2:3], v[2:3], 0, v[0:1]
	v_lshl_add_u64 v[4:5], v[4:5], 0, v[0:1]
	v_lshlrev_b32_e32 v0, 13, v187
	v_lshl_add_u32 v8, v189, 2, 0
	s_movk_i32 s0, 0x100
	v_and_b32_e32 v9, 60, v252
	v_lshlrev_b32_e32 v6, 8, v6
	s_mov_b32 s7, 0
	v_cmp_gt_u32_e32 vcc, s0, v136
	v_add3_u32 v6, v186, v9, v6
	v_lshl_or_b32 v7, v183, 3, v7
	s_lshl_b32 s3, s2, 1
	s_lshl_b32 s14, s38, 1
	s_lshl_b32 s15, s2, 2
	s_lshl_b32 s16, s38, 2
	s_lshl_b32 s17, s2, 5
	s_lshl_b32 s18, s38, 5
	s_mov_b32 s19, 0x8000
	s_mov_b32 s20, 0x40000
	s_mov_b32 s21, 0x48000
	v_add_u32_e32 v8, v8, v0
	s_mov_b32 s22, s2
	v_readlane_b32 s13, v253, 52
	v_readlane_b32 s23, v253, 62
	v_readlane_b32 s24, v253, 63
	v_readlane_b32 s25, v254, 0
	s_branch .LBB0_918
